# attention: two K/V LDS buffers - the prefetched next tile is stored into the other buffer at the end of the current tile, one barrier per tile instead of two (non-prefetched tiles keep the load/store/
# speedup vs baseline: 1.0051x; 1.0050x over previous
; DEVI unsigned pk2(float lo, float hi) { f32x2 v = {lo, hi}; bf16x2_t b = __builtin_convertvector(v, bf16x2_t); return __builtin_bit_cast(unsigned, b); }
; DEVI void attn_item(const P& p, int item, char* smem) {
;     ...
;                 float mx = s[0][0];
; #pragma unroll
;                 for (int n = 0; n < 4; ++n)
; #pragma unroll
;                     for (int j = 0; j < 4; ++j) mx = fmaxf(mx, s[n][j]);
;                 mx = rowmax4(mx);
;                 const float mnew = fmaxf(mrow[m], mx);
;                 const float alpha = __builtin_amdgcn_exp2f(mrow[m] - mnew);
;                 mrow[m] = mnew;
;                 float ls = 0.f;
; #pragma unroll
;                 for (int n = 0; n < 4; ++n)
; #pragma unroll
;                     for (int j = 0; j < 4; ++j) { s[n][j] = __builtin_amdgcn_exp2f(s[n][j] - mnew); ls += s[n][j]; }
;                 lrow[m] = lrow[m] * alpha + ls;
; #pragma unroll
;                 for (int nd = 0; nd < 4; ++nd) O[nd][m] *= alpha;
; #pragma unroll
;                 for (int kk = 0; kk < 2; ++kk) {
;                     union { uint4 u; bf16x8 v; } cv;
;                     cv.u.x = pk2(s[2 * kk][0], s[2 * kk][1]); cv.u.y = pk2(s[2 * kk][2], s[2 * kk][3]);
;                     cv.u.z = pk2(s[2 * kk + 1][0], s[2 * kk + 1][1]); cv.u.w = pk2(s[2 * kk + 1][2], s[2 * kk + 1][3]);
;                     Pf[m][kk] = cv.v;
;                 }
;             }
; #pragma unroll
;             for (int nd = 0; nd < 4; ++nd)
; #pragma unroll
;                 for (int kk = 0; kk < 2; ++kk) {
;                     const int row = 16 * nd + fr, x2 = 2 * ((row >> 1) & 7);
;                     const uint2 lo = *(const uint2*)(sV + row * 128 + (((8 * kk + fq) ^ x2) << 3));
;                     const uint2 hi = *(const uint2*)(sV + row * 128 + (((8 * kk + 4 + fq) ^ x2) << 3));
;                     union { uint4 u; bf16x8 v; } cv;
;                     cv.u.x = lo.x; cv.u.y = lo.y; cv.u.z = hi.x; cv.u.w = hi.y;
; #pragma unroll
;                     for (int m = 0; m < 2; ++m) O[nd][m] = __builtin_amdgcn_mfma_f32_16x16x32_bf16(cv.v, Pf[m][kk], O[nd][m], 0, 0, 0);
;                 }
.LBB0_1433:
	v_max3_f32 v91, v160, v86, v87
	v_sub_f32_e32 v0, v78, v91
	v_exp_f32_e32 v78, v0
	v_sub_f32_e32 v79, v79, v91
	v_exp_f32_e32 v79, v79
	v_sub_f32_e32 v80, v80, v91
	v_exp_f32_e32 v80, v80
	v_sub_f32_e32 v81, v81, v91
	v_exp_f32_e32 v81, v81
	v_sub_f32_e32 v74, v74, v91
	v_add_f32_e32 v82, 0, v78
	v_exp_f32_e32 v74, v74
	v_sub_f32_e32 v75, v75, v91
	v_add_f32_e32 v82, v79, v82
	v_exp_f32_e32 v75, v75
	v_sub_f32_e32 v76, v76, v91
	v_add_f32_e32 v82, v80, v82
	v_exp_f32_e32 v76, v76
	v_sub_f32_e32 v77, v77, v91
	v_add_f32_e32 v82, v81, v82
	v_exp_f32_e32 v77, v77
	v_sub_f32_e32 v58, v58, v91
	v_add_f32_e32 v82, v74, v82
	v_exp_f32_e32 v58, v58
	v_sub_f32_e32 v59, v59, v91
	v_add_f32_e32 v82, v75, v82
	v_exp_f32_e32 v59, v59
	v_add_f32_e32 v82, v76, v82
	v_add_f32_e32 v82, v77, v82
	v_add_f32_e32 v82, v58, v82
	v_sub_f32_e32 v50, v50, v91
	v_sub_f32_e32 v51, v51, v91
	v_exp_f32_e32 v83, v50
	v_add_f32_e32 v50, v59, v82
	v_exp_f32_e32 v82, v51
	v_sub_f32_e32 v51, v52, v91
	v_cvt_pk_bf16_f32 v52, v74, v75
	v_max_f32_e32 v74, v70, v71
	v_max3_f32 v74, v74, v72, v73
	v_max3_f32 v74, v74, v62, v63
	v_max3_f32 v74, v74, v64, v65
	v_max3_f32 v74, v74, v54, v55
	v_sub_f32_e32 v60, v60, v91
	v_max3_f32 v74, v74, v56, v57
	v_exp_f32_e32 v60, v60
	v_sub_f32_e32 v61, v61, v91
	v_max3_f32 v74, v74, v66, v67
	v_exp_f32_e32 v61, v61
	v_max3_f32 v74, v74, v68, v69
	v_mov_b32_e32 v75, v74
	s_nop 1
	v_permlane32_swap_b32_e32 v74, v75
	v_add_f32_e32 v50, v60, v50
	v_exp_f32_e32 v84, v51
	v_sub_f32_e32 v51, v53, v91
	v_sub_f32_e32 v0, v160, v91
	v_add_f32_e32 v50, v61, v50
	v_exp_f32_e32 v85, v51
	v_max_f32_e32 v74, v74, v75
	v_add_f32_e32 v50, v83, v50
	v_exp_f32_e32 v0, v0
	v_mov_b32_e32 v75, v74
	v_add_f32_e32 v50, v82, v50
	s_nop 0
	v_permlane16_swap_b32_e32 v74, v75
	v_add_f32_e32 v50, v84, v50
	v_max3_f32 v93, v159, v74, v75
	v_add_f32_e32 v92, v85, v50
	v_sub_f32_e32 v54, v54, v93
	v_fmac_f32_e32 v92, v158, v0
	v_exp_f32_e32 v158, v54
	v_sub_f32_e32 v54, v55, v93
	v_sub_f32_e32 v74, v159, v93
	v_exp_f32_e32 v159, v54
	v_sub_f32_e32 v54, v56, v93
	v_exp_f32_e32 v160, v54
	v_sub_f32_e32 v54, v57, v93
	v_sub_f32_e32 v62, v62, v93
	v_exp_f32_e32 v161, v54
	v_sub_f32_e32 v54, v66, v93
	v_exp_f32_e32 v94, v62
	v_sub_f32_e32 v62, v63, v93
	v_exp_f32_e32 v162, v54
	v_sub_f32_e32 v54, v67, v93
	v_exp_f32_e32 v95, v62
	v_sub_f32_e32 v62, v64, v93
	v_exp_f32_e32 v163, v54
	v_sub_f32_e32 v54, v68, v93
	v_exp_f32_e32 v96, v62
	v_sub_f32_e32 v62, v65, v93
	v_exp_f32_e32 v164, v54
	v_sub_f32_e32 v54, v69, v93
	v_exp_f32_e32 v97, v62
	v_exp_f32_e32 v165, v54
	ds_read_b128 v[54:57], v132 offset:8192
	ds_read_b128 v[62:65], v132 offset:10240
	v_sub_f32_e32 v70, v70, v93
	v_exp_f32_e32 v86, v70
	v_sub_f32_e32 v70, v71, v93
	v_exp_f32_e32 v87, v70
	v_sub_f32_e32 v70, v72, v93
	v_cvt_pk_bf16_f32 v50, v78, v79
	v_cvt_pk_bf16_f32 v51, v80, v81
	v_cvt_pk_bf16_f32 v53, v76, v77
	v_exp_f32_e32 v88, v70
	v_sub_f32_e32 v70, v73, v93
	v_exp_f32_e32 v90, v74
	ds_read_b128 v[74:77], v134 offset:8192
	ds_read_b128 v[78:81], v134 offset:10240
	v_exp_f32_e32 v89, v70
	s_waitcnt lgkmcnt(3)
	s_waitcnt lgkmcnt(2)
	v_pk_mul_f32 v[40:41], v[40:41], v[0:1] op_sel_hi:[1,0]
	v_pk_mul_f32 v[38:39], v[38:39], v[0:1] op_sel_hi:[1,0]
	v_pk_mul_f32 v[44:45], v[44:45], v[0:1] op_sel_hi:[1,0]
	v_pk_mul_f32 v[42:43], v[42:43], v[0:1] op_sel_hi:[1,0]
	v_cvt_pk_bf16_f32 v58, v58, v59
	v_cvt_pk_bf16_f32 v59, v60, v61
	v_cvt_pk_bf16_f32 v60, v83, v82
	v_cvt_pk_bf16_f32 v61, v84, v85
	v_pk_mul_f32 v[16:17], v[16:17], v[90:91] op_sel_hi:[1,0]
	v_pk_mul_f32 v[14:15], v[14:15], v[90:91] op_sel_hi:[1,0]
	v_cvt_pk_bf16_f32 v66, v86, v87
	v_cvt_pk_bf16_f32 v67, v88, v89
	v_cvt_pk_bf16_f32 v68, v94, v95
	v_cvt_pk_bf16_f32 v69, v96, v97
	s_waitcnt lgkmcnt(1)
	s_waitcnt lgkmcnt(0)
	v_pk_mul_f32 v[12:13], v[12:13], v[90:91] op_sel_hi:[1,0]
	v_pk_mul_f32 v[10:11], v[10:11], v[90:91] op_sel_hi:[1,0]
	v_pk_mul_f32 v[48:49], v[48:49], v[0:1] op_sel_hi:[1,0]
	v_pk_mul_f32 v[46:47], v[46:47], v[0:1] op_sel_hi:[1,0]
	v_mfma_f32_16x16x32_bf16 v[38:41], v[54:57], v[50:53], v[38:41]
	v_mul_f32_e64 v20, v20, v0
	v_mul_f32_e64 v21, v21, v0
	v_pk_mul_f32 v[18:19], v[18:19], v[0:1] op_sel_hi:[1,0]
	v_add_f32_e32 v0, 0, v86
	v_mfma_f32_16x16x32_bf16 v[14:17], v[54:57], v[66:69], v[14:17]
	ds_read_b128 v[54:57], v132 offset:12288
	v_add_f32_e32 v0, v87, v0
	v_add_f32_e32 v0, v88, v0
	v_mfma_f32_16x16x32_bf16 v[42:45], v[62:65], v[50:53], v[42:45]
	v_cvt_pk_bf16_f32 v70, v158, v159
	v_cvt_pk_bf16_f32 v71, v160, v161
	v_cvt_pk_bf16_f32 v72, v162, v163
	v_mfma_f32_16x16x32_bf16 v[10:13], v[62:65], v[66:69], v[10:13]
	ds_read_b128 v[62:65], v132 offset:14336
	v_cvt_pk_bf16_f32 v73, v164, v165
	v_add_f32_e32 v0, v89, v0
	v_mfma_f32_16x16x32_bf16 v[38:41], v[74:77], v[58:61], v[38:41]
	v_add_f32_e32 v0, v94, v0
	s_waitcnt lgkmcnt(1)
	v_mfma_f32_16x16x32_bf16 v[14:17], v[74:77], v[70:73], v[14:17]
	ds_read_b128 v[74:77], v134 offset:12288
	s_waitcnt lgkmcnt(1)
	v_mfma_f32_16x16x32_bf16 v[42:45], v[78:81], v[58:61], v[42:45]
	v_add_f32_e32 v0, v95, v0
	v_mfma_f32_16x16x32_bf16 v[10:13], v[78:81], v[70:73], v[10:13]
	ds_read_b128 v[78:81], v134 offset:14336
	v_add_f32_e32 v0, v96, v0
	v_add_f32_e32 v0, v97, v0
	v_add_f32_e32 v0, v158, v0
	v_pk_mul_f32 v[8:9], v[8:9], v[90:91] op_sel_hi:[1,0]
	v_pk_mul_f32 v[6:7], v[6:7], v[90:91] op_sel_hi:[1,0]
	s_waitcnt lgkmcnt(0)
	v_add_f32_e32 v0, v159, v0
	v_pk_mul_f32 v[4:5], v[4:5], v[90:91] op_sel_hi:[1,0]
	v_pk_mul_f32 v[2:3], v[2:3], v[90:91] op_sel_hi:[1,0]
	v_mfma_f32_16x16x32_bf16 v[46:49], v[54:57], v[50:53], v[46:49]
	v_add_f32_e32 v0, v160, v0
	v_add_f32_e32 v0, v161, v0
	v_add_f32_e32 v0, v162, v0
	v_mfma_f32_16x16x32_bf16 v[6:9], v[54:57], v[66:69], v[6:9]
	v_add_f32_e32 v0, v163, v0
	v_add_f32_e32 v0, v164, v0
	v_add_f32_e32 v0, v165, v0
	v_mfma_f32_16x16x32_bf16 v[18:21], v[62:65], v[50:53], v[18:21]
	v_fmac_f32_e32 v0, v139, v90
	v_mov_b32_e32 v159, v93
	v_mov_b32_e32 v160, v91
	v_mfma_f32_16x16x32_bf16 v[2:5], v[62:65], v[66:69], v[2:5]
	v_mov_b32_e32 v139, v0
	v_mov_b32_e32 v158, v92
	v_mfma_f32_16x16x32_bf16 v[46:49], v[74:77], v[58:61], v[46:49]
	v_mfma_f32_16x16x32_bf16 v[6:9], v[74:77], v[70:73], v[6:9]
	v_mfma_f32_16x16x32_bf16 v[18:21], v[78:81], v[58:61], v[18:21]
	v_mfma_f32_16x16x32_bf16 v[2:5], v[78:81], v[70:73], v[2:5]
	v_xor_b32_e32 v130, 0x4000, v130
	v_xor_b32_e32 v131, 0x4000, v131
	v_xor_b32_e32 v132, 0x4000, v132
	v_xor_b32_e32 v134, 0x4000, v134
	v_xor_b32_e32 v133, 0x4000, v133
	v_xor_b32_e32 v135, 0x4000, v135
	v_xor_b32_e32 v214, 0x4000, v214
	v_xor_b32_e32 v217, 0x4000, v217
	v_xor_b32_e32 v229, 0x4000, v229
	v_xor_b32_e32 v215, 0x4000, v215
	s_cmp_eq_u32 s99, 1
	s_cbranch_scc0 .Lat_endw
	s_waitcnt vmcnt(0)
	ds_write_b128 v133, v[190:193]
	ds_write_b64 v135, v[194:195] offset:8192
	ds_write_b64 v214, v[196:197] offset:8192
	ds_write_b128 v217, v[198:201]
	ds_write_b64 v229, v[202:203] offset:8192
	ds_write_b64 v215, v[204:205] offset:8192
	s_mov_b32 s99, 2
; DEVI void attn_item(const P& p, int item, char* smem) {
;     ...
;         for (int ti = 0; ti < 9; ++ti) {
;             int tok0; bool lat;
;             if (ti < 5) { const int kb = q0 - 128 + 64 * ti; if (kb < 0 || kb >= SEQ) continue; tok0 = CTX + kb; lat = true; }
;             else { tok0 = (ti - 5) * 64; lat = false; }
;             __syncthreads();
; #pragma unroll
;             for (int i = 0; i < 2; ++i) {
;                 const int row = (tid >> 3) + 32 * i, ch = tid & 7;
;                 const uint4 kv = *(const uint4*)(KB + ((size_t)(b * TPB + tok0 + row)) * 256 + kvh * 64 + ch * 8);
;                 *(uint4*)(sK + row * 128 + ((ch ^ (row & 7)) << 4)) = kv;
;                 const uint4 vv = *(const uint4*)(VT + ((size_t)(b * 256 + kvh * 64 + row)) * TPB + tok0 + ch * 8);
;                 *(uint4*)(sV + row * 128 + ((ch ^ ((row >> 1) & 7)) << 4)) = vv;
;             }
;             __syncthreads();
.Lat_endw:
	s_waitcnt lgkmcnt(0)
	s_barrier
.LBB0_1434:
	s_add_i32 s28, s28, 1
	s_add_i32 s47, s47, 64
	s_cmp_eq_u32 s28, 9
	s_cbranch_scc1 .LBB0_1431

; DEVI void attn_item(const P& p, int item, char* smem) {
;     ...
;             if (ti < 5) { const int kb = q0 - 128 + 64 * ti; if (kb < 0 || kb >= SEQ) continue; tok0 = CTX + kb; lat = true; }
;             else { tok0 = (ti - 5) * 64; lat = false; }
;             __syncthreads();
; #pragma unroll
;             for (int i = 0; i < 2; ++i) {
;                 const int row = (tid >> 3) + 32 * i, ch = tid & 7;
;                 const uint4 kv = *(const uint4*)(KB + ((size_t)(b * TPB + tok0 + row)) * 256 + kvh * 64 + ch * 8);
;                 *(uint4*)(sK + row * 128 + ((ch ^ (row & 7)) << 4)) = kv;
;                 const uint4 vv = *(const uint4*)(VT + ((size_t)(b * 256 + kvh * 64 + row)) * TPB + tok0 + ch * 8);
;                 *(uint4*)(sV + row * 128 + ((ch ^ ((row >> 1) & 7)) << 4)) = vv;
;             }
;     ...
;                 if (lat && (ti == 0 || ti == 4)) {
;                     const int qpos = q0 + mo + 16 * m + fr, kb = tok0 - CTX;
; #pragma unroll
;                     for (int n = 0; n < 4; ++n)
; #pragma unroll
;                         for (int j = 0; j < 4; ++j) {
;                             const int dd = qpos - (kb + 16 * n + 4 * fq + j);
;                             if (dd > 128 || dd < -128) s[n][j] = -1e30f;
;                         }
.LBB0_1439:
	s_andn2_b64 vcc, exec, s[4:5]
	s_cbranch_vccnz .LBB0_1434
	s_ashr_i32 s31, s30, 31
	s_cmp_eq_u32 s99, 2
	s_cbranch_scc1 .Lat_inlds
	s_mov_b32 s101, 0
	v_lshl_add_u64 v[58:59], s[30:31], 1, v[100:101]
	v_lshl_add_u64 v[54:55], v[58:59], 0, v[114:115]
	v_lshl_add_u64 v[62:63], v[58:59], 0, v[116:117]
	s_add_i32 s100, s30, s46
	s_lshl_b32 s100, s100, 9
	v_lshl_add_u64 v[50:51], v[226:227], 0, s[100:101]
	s_add_i32 s100, s100, 0x4000
	v_lshl_add_u64 v[60:61], v[226:227], 0, s[100:101]
	global_load_dwordx4 v[190:193], v[50:51], off
	global_load_dwordx4 v[194:197], v[54:55], off
	global_load_dwordx4 v[198:201], v[60:61], off
	global_load_dwordx4 v[202:205], v[62:63], off
	s_waitcnt vmcnt(0)
	ds_write_b128 v133, v[190:193]
	ds_write_b64 v135, v[194:195] offset:8192
	ds_write_b64 v214, v[196:197] offset:8192
	ds_write_b128 v217, v[198:201]
	ds_write_b64 v229, v[202:203] offset:8192
	ds_write_b64 v215, v[204:205] offset:8192
	s_waitcnt lgkmcnt(0)
	s_barrier
.Lat_inlds:
	s_and_b32 s4, s28, 11
	s_cmp_eq_u32 s4, 0
	s_cselect_b64 s[18:19], -1, 0
	s_and_b64 s[18:19], s[2:3], s[18:19]
	s_andn2_b64 vcc, exec, s[18:19]
	s_andn2_b64 s[2:3], exec, s[18:19]
	s_cbranch_vccnz .Lat_noprep
	v_sub_u32_e32 v0, s30, v140
	v_subrev_u32_e32 v171, s30, v142
	v_subrev_u32_e32 v170, s30, v143
	v_subrev_u32_e32 v168, s30, v144
	v_subrev_u32_e32 v169, s30, v145
	v_subrev_u32_e32 v165, s30, v146
	v_subrev_u32_e32 v162, s30, v147
	v_subrev_u32_e32 v166, s30, v148
	v_subrev_u32_e32 v163, s30, v149
	v_subrev_u32_e32 v167, s30, v150
	v_subrev_u32_e32 v164, s30, v151
	v_subrev_u32_e32 v161, s30, v140
	v_cmp_gt_u32_e64 s[4:5], s38, v0
	v_cmp_lt_u32_e64 s[6:7], s39, v171
	v_cmp_lt_u32_e64 s[8:9], s39, v170
	v_cmp_lt_u32_e64 s[10:11], s39, v168
	v_cmp_lt_u32_e64 s[12:13], s39, v169
	v_cmp_lt_u32_e64 s[14:15], s39, v165
	v_cmp_lt_u32_e64 s[16:17], s39, v162
	v_cmp_lt_u32_e64 s[20:21], s39, v163
	v_cmp_lt_u32_e64 s[22:23], s39, v167
	v_cmp_lt_u32_e64 s[24:25], s39, v164
	v_cmp_lt_u32_e64 s[56:57], s39, v166
.Lat_noprep:
	s_mov_b32 s99, 0
	s_cmp_lt_u32 s28, 8
	s_cbranch_scc0 .Lat_nopf
	s_cmp_gt_u32 s28, 3
	s_cbranch_scc1 .Lat_ctx
	s_add_i32 s100, s47, 64
	s_add_i32 s98, s100, 0xffffff00
	s_cmpk_lt_u32 s98, 0x1000
	s_cbranch_scc0 .Lat_nopf
	s_branch .Lat_issue

; DEVI void attn_item(const P& p, int item, char* smem) {
;     ...
;             bf16x8 Kf[4][2];
; #pragma unroll
;             for (int n = 0; n < 4; ++n)
; #pragma unroll
;                 for (int kk = 0; kk < 2; ++kk) Kf[n][kk] = *(const bf16x8*)(sK + (16 * n + fr) * 128 + (((kk * 4 + fq) ^ (fr & 7)) << 4));
;             bf16x8 Pf[2][2];
; #pragma unroll
;             for (int m = 0; m < 2; ++m) {
;                 f32x4 s[4];
; #pragma unroll
;                 for (int n = 0; n < 4; ++n) {
;                     s[n] = (f32x4){0.f, 0.f, 0.f, 0.f};
; #pragma unroll
;                     for (int kk = 0; kk < 2; ++kk) s[n] = __builtin_amdgcn_mfma_f32_16x16x32_bf16(Kf[n][kk], Qf[m][kk], s[n], 0, 0, 0);
;                 }
;                 if (lat && (ti == 0 || ti == 4)) {
;                     const int qpos = q0 + mo + 16 * m + fr, kb = tok0 - CTX;
; #pragma unroll
;                     for (int n = 0; n < 4; ++n)
; #pragma unroll
;                         for (int j = 0; j < 4; ++j) {
;                             const int dd = qpos - (kb + 16 * n + 4 * fq + j);
;                             if (dd > 128 || dd < -128) s[n][j] = -1e30f;
;                         }
;                 }
.Lat_nopf:
	ds_read_b128 v[70:73], v130
	ds_read_b128 v[62:65], v130 offset:2048
	ds_read_b128 v[54:57], v130 offset:4096
	ds_read_b128 v[82:85], v130 offset:6144
	ds_read_b128 v[94:97], v131
	ds_read_b128 v[90:93], v131 offset:2048
	ds_read_b128 v[86:89], v131 offset:4096
	ds_read_b128 v[66:69], v131 offset:6144
	s_waitcnt lgkmcnt(7)
	v_mfma_f32_16x16x32_bf16 v[50:53], v[70:73], v[22:25], 0
	s_waitcnt lgkmcnt(6)
	v_mfma_f32_16x16x32_bf16 v[58:61], v[62:65], v[22:25], 0
	s_waitcnt lgkmcnt(5)
	v_mfma_f32_16x16x32_bf16 v[182:185], v[54:57], v[22:25], 0
	s_waitcnt lgkmcnt(4)
	v_mfma_f32_16x16x32_bf16 v[186:189], v[82:85], v[22:25], 0
	s_waitcnt lgkmcnt(3)
	v_mfma_f32_16x16x32_bf16 v[78:81], v[94:97], v[26:29], v[50:53]
	s_waitcnt lgkmcnt(2)
	v_mfma_f32_16x16x32_bf16 v[74:77], v[90:93], v[26:29], v[58:61]
	s_waitcnt lgkmcnt(1)
	v_mfma_f32_16x16x32_bf16 v[58:61], v[86:89], v[26:29], v[182:185]
	s_waitcnt lgkmcnt(0)
	v_mfma_f32_16x16x32_bf16 v[50:53], v[66:69], v[26:29], v[186:189]
	s_cbranch_vccnz .LBB0_1442
	v_cmp_gt_u32_e32 vcc, s37, v161
	v_subrev_u32_e32 v173, s30, v152
	v_cndmask_b32_e64 v79, v136, v79, s[4:5]
	v_cndmask_b32_e32 v78, v78, v136, vcc
	v_cmp_lt_u32_e32 vcc, s39, v173
	v_subrev_u32_e32 v173, s30, v153
	v_cndmask_b32_e64 v80, v136, v80, s[6:7]
	v_cndmask_b32_e32 v50, v136, v50, vcc
	v_cmp_lt_u32_e32 vcc, s39, v173
	v_subrev_u32_e32 v173, s30, v154
	v_cndmask_b32_e64 v81, v136, v81, s[8:9]
	v_cndmask_b32_e32 v51, v136, v51, vcc
	v_cmp_lt_u32_e32 vcc, s39, v173
	v_subrev_u32_e32 v173, s30, v155
	v_cndmask_b32_e64 v74, v136, v74, s[10:11]
	v_cndmask_b32_e32 v52, v136, v52, vcc
	v_cmp_lt_u32_e32 vcc, s39, v173
	v_cndmask_b32_e64 v75, v136, v75, s[12:13]
	v_cndmask_b32_e64 v76, v136, v76, s[14:15]
	v_cndmask_b32_e64 v77, v136, v77, s[16:17]
	v_cndmask_b32_e64 v58, v136, v58, s[56:57]
	v_cndmask_b32_e64 v59, v136, v59, s[20:21]
	v_cndmask_b32_e64 v60, v136, v60, s[22:23]
	v_cndmask_b32_e64 v61, v136, v61, s[24:25]
	v_cndmask_b32_e32 v53, v136, v53, vcc
